# add: next chunk's Q and V loads of the retention prompt units issued right after the chunk's first barrier (hidden under the QK^T MFMA loop); sample-scan split rebalanced to 0xc00
# speedup vs baseline: 1.0175x; 1.0082x over previous
.LBB0_695:
	v_add_u32_e32 v88, v150, v149
	s_waitcnt vmcnt(0)
	ds_write_b128 v216, v[4:7]
	ds_write_b128 v217, v[8:11]
	ds_write_b128 v216, v[12:15] offset:16
	ds_write_b128 v217, v[16:19] offset:16
	ds_write_b128 v216, v[20:23] offset:32
	ds_write_b128 v217, v[24:27] offset:32
	ds_write_b128 v216, v[28:31] offset:48
	ds_write_b128 v217, v[32:35] offset:48
	ds_write_b128 v216, v[36:39] offset:64
	ds_write_b128 v217, v[40:43] offset:64
	ds_write_b128 v216, v[44:47] offset:80
	ds_write_b128 v217, v[48:51] offset:80
	ds_write_b128 v216, v[52:55] offset:96
	ds_write_b128 v217, v[56:59] offset:96
	ds_write_b128 v216, v[60:63] offset:112
	ds_write_b128 v217, v[64:67] offset:112
	ds_write_b16 v187, v72
	ds_write_b16_d16_hi v187, v72 offset:272
	ds_write_b16 v88, v73
	ds_write_b16_d16_hi v188, v73 offset:272
	v_add_u32_e32 v88, v150, v151
	ds_write_b16 v88, v74
	ds_write_b16_d16_hi v189, v74 offset:272
	v_add_u32_e32 v88, v150, v152
	s_mov_b32 s0, 0
	v_mov_b32_e32 v90, 0
	v_mov_b32_e32 v91, v129
	v_mov_b32_e32 v92, v129
	v_mov_b32_e32 v93, v129
	v_mov_b32_e32 v94, 0
	v_mov_b32_e32 v95, v129
	v_mov_b32_e32 v96, v129
	v_mov_b32_e32 v97, v129
	v_mov_b32_e32 v98, 0
	v_mov_b32_e32 v99, v129
	v_mov_b32_e32 v100, v129
	v_mov_b32_e32 v101, v129
	v_mov_b32_e32 v102, 0
	v_mov_b32_e32 v103, v129
	v_mov_b32_e32 v104, v129
	v_mov_b32_e32 v105, v129
	v_mov_b32_e32 v106, 0
	v_mov_b32_e32 v107, v129
	v_mov_b32_e32 v108, v129
	v_mov_b32_e32 v109, v129
	v_mov_b32_e32 v110, 0
	v_mov_b32_e32 v111, v129
	v_mov_b32_e32 v112, v129
	v_mov_b32_e32 v113, v129
	v_mov_b32_e32 v114, 0
	v_mov_b32_e32 v115, v129
	v_mov_b32_e32 v116, v129
	v_mov_b32_e32 v117, v129
	v_mov_b32_e32 v118, 0
	v_mov_b32_e32 v119, v129
	v_mov_b32_e32 v120, v129
	v_mov_b32_e32 v121, v129
	ds_write_b16 v88, v75
	ds_write_b16_d16_hi v190, v75 offset:272
	s_waitcnt lgkmcnt(0)
	s_barrier
	s_cmp_eq_u32 s80, 16
	s_cbranch_scc1 .Lret_pf_skip
	s_lshl_b32 s32, s80, 7
	v_add_u32_e32 v220, s32, v1
	v_ashrrev_i32_e32 v221, 31, v220
	v_lshlrev_b64 v[220:221], 13, v[220:221]
	v_lshl_add_u64 v[222:223], v[2:3], 0, v[220:221]
	v_lshl_add_u64 v[220:221], v[222:223], 0, v[214:215]
	global_load_dwordx4 v[4:7], v[220:221], off
	global_load_dwordx4 v[12:15], v[220:221], off offset:16
	global_load_dwordx4 v[20:23], v[220:221], off offset:32
	global_load_dwordx4 v[28:31], v[220:221], off offset:48
	global_load_dwordx4 v[36:39], v[220:221], off offset:64
	global_load_dwordx4 v[44:47], v[220:221], off offset:80
	global_load_dwordx4 v[52:55], v[220:221], off offset:96
	global_load_dwordx4 v[60:63], v[220:221], off offset:112
	v_lshl_add_u64 v[222:223], v[140:141], 1, v[222:223]
	s_mov_b64 s[100:101], 0x1000
	v_lshl_add_u64 v[222:223], v[222:223], 0, s[100:101]
	global_load_dwordx4 v[72:75], v[222:223], off
.Lret_pf_skip:
.LBB0_696:
	v_add_u32_e32 v133, s0, v181
	v_add_u32_e32 v135, s0, v180
	v_add_u32_e32 v88, 0x10800, v133
	ds_read_b128 v[200:203], v135
	ds_read_b128 v[204:207], v88
	ds_read_b128 v[210:213], v135 offset:8448
	v_add_u32_e32 v88, 0x12900, v133
	s_waitcnt lgkmcnt(1)
	v_mfma_f32_16x16x32_bf16 v[118:121], v[204:207], v[200:203], v[118:121]
	v_add_u32_e32 v137, 0x10840, v133
	s_addk_i32 s0, 0x80
	s_cmpk_lg_i32 s0, 0x200
	s_waitcnt lgkmcnt(0)
	v_mfma_f32_16x16x32_bf16 v[114:117], v[204:207], v[210:213], v[114:117]
	ds_read_b128 v[204:207], v88
	v_add_u32_e32 v88, 0x14a00, v133
	s_waitcnt lgkmcnt(0)
	v_mfma_f32_16x16x32_bf16 v[110:113], v[204:207], v[200:203], v[110:113]
	v_mfma_f32_16x16x32_bf16 v[106:109], v[204:207], v[210:213], v[106:109]
	ds_read_b128 v[204:207], v88
	v_add_u32_e32 v88, 0x16b00, v133
	s_waitcnt lgkmcnt(0)
	v_mfma_f32_16x16x32_bf16 v[102:105], v[204:207], v[200:203], v[102:105]
	v_mfma_f32_16x16x32_bf16 v[98:101], v[204:207], v[210:213], v[98:101]
	ds_read_b128 v[204:207], v88
	s_waitcnt lgkmcnt(0)
	v_mfma_f32_16x16x32_bf16 v[94:97], v[204:207], v[200:203], v[94:97]
	ds_read_b128 v[200:203], v135 offset:64
	v_mfma_f32_16x16x32_bf16 v[88:91], v[204:207], v[210:213], v[90:93]
	ds_read_b128 v[204:207], v137
	ds_read_b128 v[210:213], v135 offset:8512
	s_nop 0
	v_add_u32_e32 v92, 0x12940, v133
	s_waitcnt lgkmcnt(1)
	v_mfma_f32_16x16x32_bf16 v[118:121], v[204:207], v[200:203], v[118:121]
	s_waitcnt lgkmcnt(0)
	v_mfma_f32_16x16x32_bf16 v[114:117], v[204:207], v[210:213], v[114:117]
	ds_read_b128 v[204:207], v92
	v_add_u32_e32 v92, 0x14a40, v133
	s_waitcnt lgkmcnt(0)
	v_mfma_f32_16x16x32_bf16 v[110:113], v[204:207], v[200:203], v[110:113]
	v_mfma_f32_16x16x32_bf16 v[106:109], v[204:207], v[210:213], v[106:109]
	ds_read_b128 v[204:207], v92
	v_add_u32_e32 v92, 0x16b40, v133
	s_waitcnt lgkmcnt(0)
	v_mfma_f32_16x16x32_bf16 v[102:105], v[204:207], v[200:203], v[102:105]
	v_mfma_f32_16x16x32_bf16 v[98:101], v[204:207], v[210:213], v[98:101]
	ds_read_b128 v[204:207], v92
	s_waitcnt lgkmcnt(0)
	v_mfma_f32_16x16x32_bf16 v[94:97], v[204:207], v[200:203], v[94:97]
	v_mfma_f32_16x16x32_bf16 v[90:93], v[204:207], v[210:213], v[88:91]
	s_cbranch_scc1 .LBB0_696
	v_mov_b32_e32 v133, v131
	s_mov_b32 s0, 0x42fc0000
	s_barrier
	s_nop 0
	v_cmp_lt_f32_e32 vcc, s0, v133
	s_mov_b32 s0, 0
	s_nop 0
	v_cndmask_b32_e32 v88, 0, v198, vcc
	v_sub_f32_e32 v88, v88, v133
	v_exp_f32_e32 v135, v88
	v_mul_f32_e32 v88, v133, v159
	v_cndmask_b32_e32 v89, 0, v197, vcc
	v_cmp_gt_f32_e32 vcc, s96, v88
	v_ldexp_f32 v89, v135, v89
	s_nop 0
	v_cndmask_b32_e32 v88, 0, v198, vcc
	v_fmac_f32_e32 v88, v133, v159
	v_exp_f32_e32 v139, v88
	v_cndmask_b32_e32 v137, 0, v197, vcc
	v_mov_b32_e32 v88, 0
	v_ldexp_f32 v200, v139, v137
	v_mul_f32_e32 v118, v118, v200
	v_mul_f32_e32 v135, v89, v200
	v_cndmask_b32_e64 v118, v118, 0, s[16:17]
	v_mul_f32_e32 v119, v119, v135
	v_cndmask_b32_e64 v119, 0, v119, s[18:19]
	v_bfe_u32 v135, v118, 16, 1
	v_add3_u32 v118, v118, v135, s3
	v_bfe_u32 v135, v119, 16, 1
	v_lshrrev_b32_e32 v118, 16, v118
	v_add3_u32 v119, v119, v135, s3
	v_and_or_b32 v202, v119, s88, v118
	v_mul_f32_e32 v118, v89, v89
	v_mul_f32_e32 v119, v89, v118
	v_pk_mul_f32 v[200:201], v[200:201], v[118:119] op_sel_hi:[0,1]
	v_pk_mul_f32 v[120:121], v[120:121], v[200:201]
	s_nop 0
	v_cndmask_b32_e64 v121, v121, 0, s[20:21]
	v_and_b32_sdwa v135, v121, v199 dst_sel:DWORD dst_unused:UNUSED_PAD src0_sel:WORD_1 src1_sel:DWORD
	v_cndmask_b32_e64 v120, v120, 0, s[22:23]
	v_add3_u32 v121, v121, v135, s3
	v_mul_f32_e32 v135, v133, v157
	v_and_b32_sdwa v137, v120, v199 dst_sel:DWORD dst_unused:UNUSED_PAD src0_sel:WORD_1 src1_sel:DWORD
	v_cmp_gt_f32_e32 vcc, s96, v135
	v_add3_u32 v120, v120, v137, s3
	v_lshrrev_b32_e32 v120, 16, v120
	v_cndmask_b32_e32 v137, 0, v198, vcc
	v_fmac_f32_e32 v137, v133, v157
	v_exp_f32_e32 v137, v137
	v_cndmask_b32_e32 v135, 0, v197, vcc
	v_and_or_b32 v203, v121, s88, v120
	v_add_u32_e32 v120, v156, v160
	ds_write_b64 v120, v[202:203]
	v_ldexp_f32 v120, v137, v135
	v_mul_f32_e32 v121, v89, v120
	v_mul_f32_e32 v135, v115, v121
	v_mul_f32_e32 v115, v120, v119
	v_mul_f32_e32 v121, v118, v120
	v_mul_f32_e32 v117, v117, v115
	v_mov_b32_e32 v115, v116
	v_pk_mul_f32 v[114:115], v[114:115], v[120:121]
	v_cndmask_b32_e64 v116, v117, 0, s[14:15]
	v_cndmask_b32_e64 v115, v115, 0, s[10:11]
	v_and_b32_sdwa v120, v115, v199 dst_sel:DWORD dst_unused:UNUSED_PAD src0_sel:WORD_1 src1_sel:DWORD
	v_add3_u32 v115, v115, v120, s3
	v_and_b32_sdwa v120, v116, v199 dst_sel:DWORD dst_unused:UNUSED_PAD src0_sel:WORD_1 src1_sel:DWORD
	v_add3_u32 v116, v116, v120, s3
	v_and_b32_e32 v116, 0xffff0000, v116
	v_or_b32_sdwa v115, v116, v115 dst_sel:DWORD dst_unused:UNUSED_PAD src0_sel:DWORD src1_sel:WORD_1
	v_mul_f32_e32 v116, v133, v162
	v_cmp_gt_f32_e32 vcc, s96, v116
	v_cndmask_b32_e64 v114, v114, 0, s[8:9]
	v_cndmask_b32_e64 v117, 0, v135, s[12:13]
	v_cndmask_b32_e32 v120, 0, v198, vcc
	v_and_b32_sdwa v121, v114, v199 dst_sel:DWORD dst_unused:UNUSED_PAD src0_sel:WORD_1 src1_sel:DWORD
	v_fmac_f32_e32 v120, v133, v162
	v_add3_u32 v114, v114, v121, s3
	v_and_b32_sdwa v121, v117, v199 dst_sel:DWORD dst_unused:UNUSED_PAD src0_sel:WORD_1 src1_sel:DWORD
	v_exp_f32_e32 v120, v120
	v_add3_u32 v117, v117, v121, s3
	v_and_b32_e32 v117, 0xffff0000, v117
	v_cndmask_b32_e32 v116, 0, v197, vcc
	v_or_b32_sdwa v114, v117, v114 dst_sel:DWORD dst_unused:UNUSED_PAD src0_sel:DWORD src1_sel:WORD_1
	v_add_u32_e32 v117, v156, v158
	ds_write_b64 v117, v[114:115]
	v_ldexp_f32 v114, v120, v116
	v_mul_f32_e32 v115, v89, v114
	v_mul_f32_e32 v116, v111, v115
	v_mul_f32_e32 v111, v114, v119
	v_mul_f32_e32 v115, v118, v114
	v_mul_f32_e32 v113, v113, v111
	v_mov_b32_e32 v111, v112
	v_pk_mul_f32 v[110:111], v[110:111], v[114:115]
	v_cndmask_b32_e64 v112, v113, 0, s[28:29]
	v_cndmask_b32_e64 v111, v111, 0, s[24:25]
	v_and_b32_sdwa v114, v111, v199 dst_sel:DWORD dst_unused:UNUSED_PAD src0_sel:WORD_1 src1_sel:DWORD
	v_add3_u32 v111, v111, v114, s3
	v_and_b32_sdwa v114, v112, v199 dst_sel:DWORD dst_unused:UNUSED_PAD src0_sel:WORD_1 src1_sel:DWORD
	v_add3_u32 v112, v112, v114, s3
	v_and_b32_e32 v112, 0xffff0000, v112
	v_or_b32_sdwa v111, v112, v111 dst_sel:DWORD dst_unused:UNUSED_PAD src0_sel:DWORD src1_sel:WORD_1
	v_mul_f32_e32 v112, v133, v163
	v_cmp_gt_f32_e32 vcc, s96, v112
	v_cndmask_b32_e64 v110, v110, 0, s[26:27]
	v_cndmask_b32_e64 v113, 0, v116, s[30:31]
	v_cndmask_b32_e32 v114, 0, v198, vcc
	v_and_b32_sdwa v115, v110, v199 dst_sel:DWORD dst_unused:UNUSED_PAD src0_sel:WORD_1 src1_sel:DWORD
	v_fmac_f32_e32 v114, v133, v163
	v_add3_u32 v110, v110, v115, s3
	v_and_b32_sdwa v115, v113, v199 dst_sel:DWORD dst_unused:UNUSED_PAD src0_sel:WORD_1 src1_sel:DWORD
	v_exp_f32_e32 v114, v114
	v_add3_u32 v113, v113, v115, s3
	v_and_b32_e32 v113, 0xffff0000, v113
	v_cndmask_b32_e32 v112, 0, v197, vcc
	v_or_b32_sdwa v110, v113, v110 dst_sel:DWORD dst_unused:UNUSED_PAD src0_sel:DWORD src1_sel:WORD_1
	v_add_u32_e32 v113, v161, v160
	ds_write_b64 v113, v[110:111]
	v_ldexp_f32 v110, v114, v112
	v_mul_f32_e32 v111, v89, v110
	v_mul_f32_e32 v112, v107, v111
	v_mul_f32_e32 v107, v110, v119
	v_mul_f32_e32 v111, v118, v110
	v_mul_f32_e32 v109, v109, v107
	v_mov_b32_e32 v107, v108
	v_pk_mul_f32 v[106:107], v[106:107], v[110:111]
	v_cndmask_b32_e64 v108, v109, 0, s[38:39]
	v_cndmask_b32_e64 v107, v107, 0, s[34:35]
	v_and_b32_sdwa v110, v107, v199 dst_sel:DWORD dst_unused:UNUSED_PAD src0_sel:WORD_1 src1_sel:DWORD
	v_add3_u32 v107, v107, v110, s3
	v_and_b32_sdwa v110, v108, v199 dst_sel:DWORD dst_unused:UNUSED_PAD src0_sel:WORD_1 src1_sel:DWORD
	v_add3_u32 v108, v108, v110, s3
	v_and_b32_e32 v108, 0xffff0000, v108
	v_or_b32_sdwa v107, v108, v107 dst_sel:DWORD dst_unused:UNUSED_PAD src0_sel:DWORD src1_sel:WORD_1
	v_mul_f32_e32 v108, v133, v165
	v_cmp_gt_f32_e32 vcc, s96, v108
	v_cndmask_b32_e64 v106, v106, 0, s[36:37]
	v_cndmask_b32_e64 v109, 0, v112, s[40:41]
	v_cndmask_b32_e32 v110, 0, v198, vcc
	v_and_b32_sdwa v111, v106, v199 dst_sel:DWORD dst_unused:UNUSED_PAD src0_sel:WORD_1 src1_sel:DWORD
	v_fmac_f32_e32 v110, v133, v165
	v_add3_u32 v106, v106, v111, s3
	v_and_b32_sdwa v111, v109, v199 dst_sel:DWORD dst_unused:UNUSED_PAD src0_sel:WORD_1 src1_sel:DWORD
	v_exp_f32_e32 v110, v110
	v_add3_u32 v109, v109, v111, s3
	v_and_b32_e32 v109, 0xffff0000, v109
	v_cndmask_b32_e32 v108, 0, v197, vcc
	v_or_b32_sdwa v106, v109, v106 dst_sel:DWORD dst_unused:UNUSED_PAD src0_sel:DWORD src1_sel:WORD_1
	v_add_u32_e32 v109, v161, v158
	ds_write_b64 v109, v[106:107]
	v_ldexp_f32 v106, v110, v108
	v_mul_f32_e32 v107, v89, v106
	v_mul_f32_e32 v108, v103, v107
	v_mul_f32_e32 v103, v106, v119
	v_mul_f32_e32 v107, v118, v106
	v_mul_f32_e32 v105, v105, v103
	v_mov_b32_e32 v103, v104
	v_pk_mul_f32 v[102:103], v[102:103], v[106:107]
	v_cndmask_b32_e64 v104, v105, 0, s[48:49]
	v_cndmask_b32_e64 v103, v103, 0, s[42:43]
	v_and_b32_sdwa v106, v103, v199 dst_sel:DWORD dst_unused:UNUSED_PAD src0_sel:WORD_1 src1_sel:DWORD
	v_add3_u32 v103, v103, v106, s3
	v_and_b32_sdwa v106, v104, v199 dst_sel:DWORD dst_unused:UNUSED_PAD src0_sel:WORD_1 src1_sel:DWORD
	v_add3_u32 v104, v104, v106, s3
	v_and_b32_e32 v104, 0xffff0000, v104
	v_or_b32_sdwa v103, v104, v103 dst_sel:DWORD dst_unused:UNUSED_PAD src0_sel:DWORD src1_sel:WORD_1
	v_mul_f32_e32 v104, v133, v166
	v_cmp_gt_f32_e32 vcc, s96, v104
	v_cndmask_b32_e64 v102, v102, 0, s[44:45]
	v_cndmask_b32_e64 v105, 0, v108, s[46:47]
	v_cndmask_b32_e32 v106, 0, v198, vcc
	v_and_b32_sdwa v107, v102, v199 dst_sel:DWORD dst_unused:UNUSED_PAD src0_sel:WORD_1 src1_sel:DWORD
	v_fmac_f32_e32 v106, v133, v166
	v_add3_u32 v102, v102, v107, s3
	v_and_b32_sdwa v107, v105, v199 dst_sel:DWORD dst_unused:UNUSED_PAD src0_sel:WORD_1 src1_sel:DWORD
	v_exp_f32_e32 v106, v106
	v_add3_u32 v105, v105, v107, s3
	v_and_b32_e32 v105, 0xffff0000, v105
	v_cndmask_b32_e32 v104, 0, v197, vcc
	v_or_b32_sdwa v102, v105, v102 dst_sel:DWORD dst_unused:UNUSED_PAD src0_sel:DWORD src1_sel:WORD_1
	v_add_u32_e32 v105, v164, v160
	ds_write_b64 v105, v[102:103]
	v_ldexp_f32 v102, v106, v104
	v_mul_f32_e32 v103, v89, v102
	v_mul_f32_e32 v104, v99, v103
	v_mul_f32_e32 v99, v102, v119
	v_mul_f32_e32 v103, v118, v102
	v_mul_f32_e32 v101, v101, v99
	v_mov_b32_e32 v99, v100
	v_pk_mul_f32 v[98:99], v[98:99], v[102:103]
	v_cndmask_b32_e64 v100, v101, 0, s[54:55]
	v_cndmask_b32_e64 v99, v99, 0, s[50:51]
	v_and_b32_sdwa v102, v99, v199 dst_sel:DWORD dst_unused:UNUSED_PAD src0_sel:WORD_1 src1_sel:DWORD
	v_add3_u32 v99, v99, v102, s3
	v_and_b32_sdwa v102, v100, v199 dst_sel:DWORD dst_unused:UNUSED_PAD src0_sel:WORD_1 src1_sel:DWORD
	v_add3_u32 v100, v100, v102, s3
	v_and_b32_e32 v100, 0xffff0000, v100
	v_or_b32_sdwa v99, v100, v99 dst_sel:DWORD dst_unused:UNUSED_PAD src0_sel:DWORD src1_sel:WORD_1
	v_mul_f32_e32 v100, v133, v168
	v_cmp_gt_f32_e32 vcc, s96, v100
	v_cndmask_b32_e64 v98, v98, 0, s[52:53]
	v_cndmask_b32_e64 v101, 0, v104, s[56:57]
	v_cndmask_b32_e32 v102, 0, v198, vcc
	v_and_b32_sdwa v103, v98, v199 dst_sel:DWORD dst_unused:UNUSED_PAD src0_sel:WORD_1 src1_sel:DWORD
	v_fmac_f32_e32 v102, v133, v168
	v_add3_u32 v98, v98, v103, s3
	v_and_b32_sdwa v103, v101, v199 dst_sel:DWORD dst_unused:UNUSED_PAD src0_sel:WORD_1 src1_sel:DWORD
	v_exp_f32_e32 v102, v102
	v_add3_u32 v101, v101, v103, s3
	v_and_b32_e32 v101, 0xffff0000, v101
	v_cndmask_b32_e32 v100, 0, v197, vcc
	v_or_b32_sdwa v98, v101, v98 dst_sel:DWORD dst_unused:UNUSED_PAD src0_sel:DWORD src1_sel:WORD_1
	v_add_u32_e32 v101, v164, v158
	ds_write_b64 v101, v[98:99]
	v_ldexp_f32 v98, v102, v100
	v_mul_f32_e32 v99, v89, v98
	v_mul_f32_e32 v100, v95, v99
	v_mul_f32_e32 v95, v98, v119
	v_mul_f32_e32 v99, v118, v98
	v_mul_f32_e32 v97, v97, v95
	v_mov_b32_e32 v95, v96
	v_pk_mul_f32 v[94:95], v[94:95], v[98:99]
	v_cndmask_b32_e64 v96, v97, 0, s[64:65]
	v_cndmask_b32_e64 v95, v95, 0, s[58:59]
	v_and_b32_sdwa v98, v95, v199 dst_sel:DWORD dst_unused:UNUSED_PAD src0_sel:WORD_1 src1_sel:DWORD
	v_add3_u32 v95, v95, v98, s3
	v_and_b32_sdwa v98, v96, v199 dst_sel:DWORD dst_unused:UNUSED_PAD src0_sel:WORD_1 src1_sel:DWORD
	v_add3_u32 v96, v96, v98, s3
	v_and_b32_e32 v96, 0xffff0000, v96
	v_or_b32_sdwa v95, v96, v95 dst_sel:DWORD dst_unused:UNUSED_PAD src0_sel:DWORD src1_sel:WORD_1
	v_mul_f32_e32 v96, v133, v169
	v_cmp_gt_f32_e32 vcc, s96, v96
	v_cndmask_b32_e64 v94, v94, 0, s[60:61]
	v_cndmask_b32_e64 v97, 0, v100, s[62:63]
	v_cndmask_b32_e32 v98, 0, v198, vcc
	v_and_b32_sdwa v99, v94, v199 dst_sel:DWORD dst_unused:UNUSED_PAD src0_sel:WORD_1 src1_sel:DWORD
	v_fmac_f32_e32 v98, v133, v169
	v_add3_u32 v94, v94, v99, s3
	v_and_b32_sdwa v99, v97, v199 dst_sel:DWORD dst_unused:UNUSED_PAD src0_sel:WORD_1 src1_sel:DWORD
	v_exp_f32_e32 v98, v98
	v_add3_u32 v97, v97, v99, s3
	v_and_b32_e32 v97, 0xffff0000, v97
	v_cndmask_b32_e32 v96, 0, v197, vcc
	v_or_b32_sdwa v94, v97, v94 dst_sel:DWORD dst_unused:UNUSED_PAD src0_sel:DWORD src1_sel:WORD_1
	v_add_u32_e32 v97, v167, v160
	ds_write_b64 v97, v[94:95]
	v_ldexp_f32 v94, v98, v96
	v_mul_f32_e32 v89, v89, v94
	v_mul_f32_e32 v89, v91, v89
	v_mul_f32_e32 v91, v94, v119
	v_mul_f32_e32 v95, v118, v94
	v_mul_f32_e32 v93, v93, v91
	v_mov_b32_e32 v91, v92
	v_pk_mul_f32 v[90:91], v[90:91], v[94:95]
	v_cndmask_b32_e64 v92, v93, 0, s[70:71]
	v_cndmask_b32_e64 v90, v90, 0, s[68:69]
	v_cndmask_b32_e64 v91, v91, 0, s[66:67]
	v_cndmask_b32_e64 v89, 0, v89, s[72:73]
	v_and_b32_sdwa v93, v91, v199 dst_sel:DWORD dst_unused:UNUSED_PAD src0_sel:WORD_1 src1_sel:DWORD
	v_and_b32_sdwa v94, v90, v199 dst_sel:DWORD dst_unused:UNUSED_PAD src0_sel:WORD_1 src1_sel:DWORD
	v_add3_u32 v90, v90, v94, s3
	v_add3_u32 v91, v91, v93, s3
	v_and_b32_sdwa v93, v92, v199 dst_sel:DWORD dst_unused:UNUSED_PAD src0_sel:WORD_1 src1_sel:DWORD
	v_and_b32_sdwa v94, v89, v199 dst_sel:DWORD dst_unused:UNUSED_PAD src0_sel:WORD_1 src1_sel:DWORD
	v_add3_u32 v92, v92, v93, s3
	v_add3_u32 v89, v89, v94, s3
	v_and_b32_e32 v92, 0xffff0000, v92
	v_and_b32_e32 v89, 0xffff0000, v89
	v_or_b32_sdwa v91, v92, v91 dst_sel:DWORD dst_unused:UNUSED_PAD src0_sel:DWORD src1_sel:WORD_1
	v_or_b32_sdwa v90, v89, v90 dst_sel:DWORD dst_unused:UNUSED_PAD src0_sel:DWORD src1_sel:WORD_1
	v_add_u32_e32 v89, v167, v158
	ds_write_b64 v89, v[90:91]
	v_bfe_u32 v89, v84, 16, 1
	v_add3_u32 v89, v84, v89, s3
	v_bfe_u32 v90, v85, 16, 1
	v_lshrrev_b32_e32 v89, 16, v89
	v_add3_u32 v90, v85, v90, s3
	v_and_or_b32 v90, v90, s88, v89
	v_bfe_u32 v89, v86, 16, 1
	v_add3_u32 v89, v86, v89, s3
	v_bfe_u32 v91, v87, 16, 1
	v_lshrrev_b32_e32 v89, 16, v89
	v_add3_u32 v91, v87, v91, s3
	v_and_or_b32 v91, v91, s88, v89
	v_add_u32_e32 v89, v146, v153
	ds_write_b64 v89, v[90:91]
	v_bfe_u32 v90, v80, 16, 1
	v_add3_u32 v90, v80, v90, s3
	v_bfe_u32 v91, v81, 16, 1
	v_lshrrev_b32_e32 v90, 16, v90
	v_add3_u32 v91, v81, v91, s3
	v_and_or_b32 v90, v91, s88, v90
	v_bfe_u32 v91, v82, 16, 1
	v_add3_u32 v91, v82, v91, s3
	v_bfe_u32 v92, v83, 16, 1
	v_lshrrev_b32_e32 v91, 16, v91
	v_add3_u32 v92, v83, v92, s3
	v_and_or_b32 v91, v92, s88, v91
	ds_write_b64 v191, v[90:91]
	v_bfe_u32 v90, v76, 16, 1
	v_add3_u32 v90, v76, v90, s3
	v_bfe_u32 v91, v77, 16, 1
	v_lshrrev_b32_e32 v90, 16, v90
	v_add3_u32 v91, v77, v91, s3
	v_and_or_b32 v90, v91, s88, v90
	v_bfe_u32 v91, v78, 16, 1
	v_add3_u32 v91, v78, v91, s3
	v_bfe_u32 v92, v79, 16, 1
	v_lshrrev_b32_e32 v91, 16, v91
	v_add3_u32 v92, v79, v92, s3
	v_and_or_b32 v91, v92, s88, v91
	ds_write_b64 v89, v[90:91] offset:32
	v_bfe_u32 v89, v68, 16, 1
	v_add3_u32 v89, v68, v89, s3
	v_bfe_u32 v90, v69, 16, 1
	v_lshrrev_b32_e32 v89, 16, v89
	v_add3_u32 v90, v69, v90, s3
	v_and_or_b32 v90, v90, s88, v89
	v_bfe_u32 v89, v70, 16, 1
	v_add3_u32 v89, v70, v89, s3
	v_bfe_u32 v91, v71, 16, 1
	v_lshrrev_b32_e32 v89, 16, v89
	v_add3_u32 v91, v71, v91, s3
	v_and_or_b32 v91, v91, s88, v89
	ds_write_b64 v191, v[90:91] offset:32
	v_mov_b32_e32 v89, v88
	v_mov_b32_e32 v90, v88
	v_mov_b32_e32 v91, v88
	v_mov_b32_e32 v96, v88
	v_mov_b32_e32 v97, v88
	v_mov_b32_e32 v98, v88
	v_mov_b32_e32 v99, v88
	s_waitcnt lgkmcnt(0)
	s_barrier

.LBB0_713:
	s_or_b64 exec, exec, s[0:1]
	v_add_u32_e32 v88, s2, v148
	v_cvt_f32_i32_e32 v88, v88
	s_barrier
	v_mul_f32_e32 v89, v133, v88
	v_cmp_gt_f32_e32 vcc, s96, v89
	s_cmp_eq_u32 s80, 16
	s_nop 0
	v_cndmask_b32_e32 v89, 0, v198, vcc
	v_fmac_f32_e32 v89, v133, v88
	v_exp_f32_e32 v88, v89
	v_cndmask_b32_e32 v89, 0, v197, vcc
	v_cmp_gt_u32_e32 vcc, s2, v145
	v_ldexp_f32 v88, v88, v89
	s_nop 0
	v_cndmask_b32_e32 v88, 0, v88, vcc
	v_lshlrev_b32_e32 v89, 16, v8
	v_mul_f32_e32 v89, v88, v89
	v_bfe_u32 v90, v89, 16, 1
	v_add3_u32 v89, v89, v90, s3
	ds_write_b16_d16_hi v218, v89
	v_and_b32_e32 v89, 0xffff0000, v8
	v_mul_f32_e32 v89, v88, v89
	v_bfe_u32 v90, v89, 16, 1
	v_add3_u32 v89, v89, v90, s3
	ds_write_b16_d16_hi v218, v89 offset:272
	v_lshlrev_b32_e32 v89, 16, v9
	v_mul_f32_e32 v89, v88, v89
	v_bfe_u32 v90, v89, 16, 1
	v_add3_u32 v89, v89, v90, s3
	v_add_u32_e32 v90, v176, v149
	ds_write_b16_d16_hi v218, v89 offset:544
	v_and_b32_e32 v89, 0xffff0000, v9
	v_mul_f32_e32 v89, v88, v89
	v_bfe_u32 v90, v89, 16, 1
	v_add3_u32 v89, v89, v90, s3
	ds_write_b16_d16_hi v218, v89 offset:816
	v_lshlrev_b32_e32 v89, 16, v10
	v_mul_f32_e32 v89, v88, v89
	v_bfe_u32 v90, v89, 16, 1
	v_add3_u32 v89, v89, v90, s3
	v_add_u32_e32 v90, v176, v151
	ds_write_b16_d16_hi v218, v89 offset:1088
	v_and_b32_e32 v89, 0xffff0000, v10
	v_mul_f32_e32 v89, v88, v89
	v_bfe_u32 v90, v89, 16, 1
	v_add3_u32 v89, v89, v90, s3
	ds_write_b16_d16_hi v218, v89 offset:1360
	v_lshlrev_b32_e32 v89, 16, v11
	v_mul_f32_e32 v89, v88, v89
	v_bfe_u32 v90, v89, 16, 1
	v_add3_u32 v89, v89, v90, s3
	v_add_u32_e32 v90, v176, v152
	ds_write_b16_d16_hi v218, v89 offset:1632
	v_and_b32_e32 v89, 0xffff0000, v11
	v_mul_f32_e32 v89, v88, v89
	v_bfe_u32 v90, v89, 16, 1
	v_add3_u32 v89, v89, v90, s3
	ds_write_b16_d16_hi v218, v89 offset:1904
	v_lshlrev_b32_e32 v89, 16, v16
	v_mul_f32_e32 v89, v88, v89
	v_bfe_u32 v90, v89, 16, 1
	v_add3_u32 v89, v89, v90, s3
	ds_write_b16_d16_hi v218, v89 offset:2176
	v_and_b32_e32 v89, 0xffff0000, v16
	v_mul_f32_e32 v89, v88, v89
	v_bfe_u32 v90, v89, 16, 1
	v_add3_u32 v89, v89, v90, s3
	ds_write_b16_d16_hi v218, v89 offset:2448
	v_lshlrev_b32_e32 v89, 16, v17
	v_mul_f32_e32 v89, v88, v89
	v_bfe_u32 v90, v89, 16, 1
	v_add3_u32 v89, v89, v90, s3
	ds_write_b16_d16_hi v218, v89 offset:2720
	v_and_b32_e32 v89, 0xffff0000, v17
	v_mul_f32_e32 v89, v88, v89
	v_bfe_u32 v90, v89, 16, 1
	v_add3_u32 v89, v89, v90, s3
	ds_write_b16_d16_hi v218, v89 offset:2992
	v_lshlrev_b32_e32 v89, 16, v18
	v_mul_f32_e32 v89, v88, v89
	v_bfe_u32 v90, v89, 16, 1
	v_add3_u32 v89, v89, v90, s3
	ds_write_b16_d16_hi v218, v89 offset:3264
	v_and_b32_e32 v89, 0xffff0000, v18
	v_mul_f32_e32 v89, v88, v89
	v_bfe_u32 v90, v89, 16, 1
	v_add3_u32 v89, v89, v90, s3
	ds_write_b16_d16_hi v218, v89 offset:3536
	v_lshlrev_b32_e32 v89, 16, v19
	v_mul_f32_e32 v89, v88, v89
	v_bfe_u32 v90, v89, 16, 1
	v_add3_u32 v89, v89, v90, s3
	ds_write_b16_d16_hi v218, v89 offset:3808
	v_and_b32_e32 v89, 0xffff0000, v19
	v_mul_f32_e32 v89, v88, v89
	v_bfe_u32 v90, v89, 16, 1
	v_add3_u32 v89, v89, v90, s3
	ds_write_b16_d16_hi v218, v89 offset:4080
	v_lshlrev_b32_e32 v89, 16, v24
	v_mul_f32_e32 v89, v88, v89
	v_bfe_u32 v90, v89, 16, 1
	v_add3_u32 v89, v89, v90, s3
	ds_write_b16_d16_hi v218, v89 offset:4352
	v_and_b32_e32 v89, 0xffff0000, v24
	v_mul_f32_e32 v89, v88, v89
	v_bfe_u32 v90, v89, 16, 1
	v_add3_u32 v89, v89, v90, s3
	ds_write_b16_d16_hi v218, v89 offset:4624
	v_lshlrev_b32_e32 v89, 16, v25
	v_mul_f32_e32 v89, v88, v89
	v_bfe_u32 v90, v89, 16, 1
	v_add3_u32 v89, v89, v90, s3
	ds_write_b16_d16_hi v218, v89 offset:4896
	v_and_b32_e32 v89, 0xffff0000, v25
	v_mul_f32_e32 v89, v88, v89
	v_bfe_u32 v90, v89, 16, 1
	v_add3_u32 v89, v89, v90, s3
	ds_write_b16_d16_hi v218, v89 offset:5168
	v_lshlrev_b32_e32 v89, 16, v26
	v_mul_f32_e32 v89, v88, v89
	v_bfe_u32 v90, v89, 16, 1
	v_add3_u32 v89, v89, v90, s3
	ds_write_b16_d16_hi v218, v89 offset:5440
	v_and_b32_e32 v89, 0xffff0000, v26
	v_mul_f32_e32 v89, v88, v89
	v_bfe_u32 v90, v89, 16, 1
	v_add3_u32 v89, v89, v90, s3
	ds_write_b16_d16_hi v218, v89 offset:5712
	v_lshlrev_b32_e32 v89, 16, v27
	v_mul_f32_e32 v89, v88, v89
	v_bfe_u32 v90, v89, 16, 1
	v_add3_u32 v89, v89, v90, s3
	ds_write_b16_d16_hi v218, v89 offset:5984
	v_and_b32_e32 v89, 0xffff0000, v27
	v_mul_f32_e32 v89, v88, v89
	v_bfe_u32 v90, v89, 16, 1
	v_add3_u32 v89, v89, v90, s3
	ds_write_b16_d16_hi v218, v89 offset:6256
	v_lshlrev_b32_e32 v89, 16, v32
	v_mul_f32_e32 v89, v88, v89
	v_bfe_u32 v90, v89, 16, 1
	v_add3_u32 v89, v89, v90, s3
	ds_write_b16_d16_hi v218, v89 offset:6528
	v_and_b32_e32 v89, 0xffff0000, v32
	v_mul_f32_e32 v89, v88, v89
	v_bfe_u32 v90, v89, 16, 1
	v_add3_u32 v89, v89, v90, s3
	ds_write_b16_d16_hi v218, v89 offset:6800
	v_lshlrev_b32_e32 v89, 16, v33
	v_mul_f32_e32 v89, v88, v89
	v_bfe_u32 v90, v89, 16, 1
	v_add3_u32 v89, v89, v90, s3
	ds_write_b16_d16_hi v218, v89 offset:7072
	v_and_b32_e32 v89, 0xffff0000, v33
	v_mul_f32_e32 v89, v88, v89
	v_bfe_u32 v90, v89, 16, 1
	v_add3_u32 v89, v89, v90, s3
	ds_write_b16_d16_hi v218, v89 offset:7344
	v_lshlrev_b32_e32 v89, 16, v34
	v_mul_f32_e32 v89, v88, v89
	v_bfe_u32 v90, v89, 16, 1
	v_add3_u32 v89, v89, v90, s3
	ds_write_b16_d16_hi v218, v89 offset:7616
	v_and_b32_e32 v89, 0xffff0000, v34
	v_mul_f32_e32 v89, v88, v89
	v_bfe_u32 v90, v89, 16, 1
	v_add3_u32 v89, v89, v90, s3
	ds_write_b16_d16_hi v218, v89 offset:7888
	v_lshlrev_b32_e32 v89, 16, v35
	v_mul_f32_e32 v89, v88, v89
	v_bfe_u32 v90, v89, 16, 1
	v_add3_u32 v89, v89, v90, s3
	ds_write_b16_d16_hi v218, v89 offset:8160
	v_and_b32_e32 v89, 0xffff0000, v35
	v_mul_f32_e32 v89, v88, v89
	v_bfe_u32 v90, v89, 16, 1
	v_add3_u32 v89, v89, v90, s3
	ds_write_b16_d16_hi v218, v89 offset:8432
	v_lshlrev_b32_e32 v89, 16, v40
	v_mul_f32_e32 v89, v88, v89
	v_bfe_u32 v90, v89, 16, 1
	v_add3_u32 v89, v89, v90, s3
	ds_write_b16_d16_hi v218, v89 offset:8704
	v_and_b32_e32 v89, 0xffff0000, v40
	v_mul_f32_e32 v89, v88, v89
	v_bfe_u32 v90, v89, 16, 1
	v_add3_u32 v89, v89, v90, s3
	ds_write_b16_d16_hi v218, v89 offset:8976
	v_lshlrev_b32_e32 v89, 16, v41
	v_mul_f32_e32 v89, v88, v89
	v_bfe_u32 v90, v89, 16, 1
	v_add3_u32 v89, v89, v90, s3
	ds_write_b16_d16_hi v218, v89 offset:9248
	v_and_b32_e32 v89, 0xffff0000, v41
	v_mul_f32_e32 v89, v88, v89
	v_bfe_u32 v90, v89, 16, 1
	v_add3_u32 v89, v89, v90, s3
	ds_write_b16_d16_hi v218, v89 offset:9520
	v_lshlrev_b32_e32 v89, 16, v42
	v_mul_f32_e32 v89, v88, v89
	v_bfe_u32 v90, v89, 16, 1
	v_add3_u32 v89, v89, v90, s3
	ds_write_b16_d16_hi v218, v89 offset:9792
	v_and_b32_e32 v89, 0xffff0000, v42
	v_mul_f32_e32 v89, v88, v89
	v_bfe_u32 v90, v89, 16, 1
	v_add3_u32 v89, v89, v90, s3
	ds_write_b16_d16_hi v218, v89 offset:10064
	v_lshlrev_b32_e32 v89, 16, v43
	v_mul_f32_e32 v89, v88, v89
	v_bfe_u32 v90, v89, 16, 1
	v_add3_u32 v89, v89, v90, s3
	ds_write_b16_d16_hi v218, v89 offset:10336
	v_and_b32_e32 v89, 0xffff0000, v43
	v_mul_f32_e32 v89, v88, v89
	v_bfe_u32 v90, v89, 16, 1
	v_add3_u32 v89, v89, v90, s3
	ds_write_b16_d16_hi v218, v89 offset:10608
	v_lshlrev_b32_e32 v89, 16, v48
	v_mul_f32_e32 v89, v88, v89
	v_bfe_u32 v90, v89, 16, 1
	v_add3_u32 v89, v89, v90, s3
	ds_write_b16_d16_hi v218, v89 offset:10880
	v_and_b32_e32 v89, 0xffff0000, v48
	v_mul_f32_e32 v89, v88, v89
	v_bfe_u32 v90, v89, 16, 1
	v_add3_u32 v89, v89, v90, s3
	ds_write_b16_d16_hi v218, v89 offset:11152
	v_lshlrev_b32_e32 v89, 16, v49
	v_mul_f32_e32 v89, v88, v89
	v_bfe_u32 v90, v89, 16, 1
	v_add3_u32 v89, v89, v90, s3
	ds_write_b16_d16_hi v218, v89 offset:11424
	v_and_b32_e32 v89, 0xffff0000, v49
	v_mul_f32_e32 v89, v88, v89
	v_bfe_u32 v90, v89, 16, 1
	v_add3_u32 v89, v89, v90, s3
	ds_write_b16_d16_hi v218, v89 offset:11696
	v_lshlrev_b32_e32 v89, 16, v50
	v_mul_f32_e32 v89, v88, v89
	v_bfe_u32 v90, v89, 16, 1
	v_add3_u32 v89, v89, v90, s3
	ds_write_b16_d16_hi v218, v89 offset:11968
	v_and_b32_e32 v89, 0xffff0000, v50
	v_mul_f32_e32 v89, v88, v89
	v_bfe_u32 v90, v89, 16, 1
	v_add3_u32 v89, v89, v90, s3
	ds_write_b16_d16_hi v218, v89 offset:12240
	v_lshlrev_b32_e32 v89, 16, v51
	v_mul_f32_e32 v89, v88, v89
	v_bfe_u32 v90, v89, 16, 1
	v_add3_u32 v89, v89, v90, s3
	ds_write_b16_d16_hi v218, v89 offset:12512
	v_and_b32_e32 v89, 0xffff0000, v51
	v_mul_f32_e32 v89, v88, v89
	v_bfe_u32 v90, v89, 16, 1
	v_add3_u32 v89, v89, v90, s3
	ds_write_b16_d16_hi v218, v89 offset:12784
	v_lshlrev_b32_e32 v89, 16, v56
	v_mul_f32_e32 v89, v88, v89
	v_bfe_u32 v90, v89, 16, 1
	v_add3_u32 v89, v89, v90, s3
	ds_write_b16_d16_hi v218, v89 offset:13056
	v_and_b32_e32 v89, 0xffff0000, v56
	v_mul_f32_e32 v89, v88, v89
	v_bfe_u32 v90, v89, 16, 1
	v_add3_u32 v89, v89, v90, s3
	ds_write_b16_d16_hi v218, v89 offset:13328
	v_lshlrev_b32_e32 v89, 16, v57
	v_mul_f32_e32 v89, v88, v89
	v_bfe_u32 v90, v89, 16, 1
	v_add3_u32 v89, v89, v90, s3
	ds_write_b16_d16_hi v218, v89 offset:13600
	v_and_b32_e32 v89, 0xffff0000, v57
	v_mul_f32_e32 v89, v88, v89
	v_bfe_u32 v90, v89, 16, 1
	v_add3_u32 v89, v89, v90, s3
	ds_write_b16_d16_hi v218, v89 offset:13872
	v_lshlrev_b32_e32 v89, 16, v58
	v_mul_f32_e32 v89, v88, v89
	v_bfe_u32 v90, v89, 16, 1
	v_add3_u32 v89, v89, v90, s3
	ds_write_b16_d16_hi v218, v89 offset:14144
	v_and_b32_e32 v89, 0xffff0000, v58
	v_mul_f32_e32 v89, v88, v89
	v_bfe_u32 v90, v89, 16, 1
	v_add3_u32 v89, v89, v90, s3
	ds_write_b16_d16_hi v218, v89 offset:14416
	v_lshlrev_b32_e32 v89, 16, v59
	v_mul_f32_e32 v89, v88, v89
	v_bfe_u32 v90, v89, 16, 1
	v_add3_u32 v89, v89, v90, s3
	ds_write_b16_d16_hi v218, v89 offset:14688
	v_and_b32_e32 v89, 0xffff0000, v59
	v_mul_f32_e32 v89, v88, v89
	v_bfe_u32 v90, v89, 16, 1
	v_add3_u32 v89, v89, v90, s3
	ds_write_b16_d16_hi v218, v89 offset:14960
	v_lshlrev_b32_e32 v89, 16, v64
	v_mul_f32_e32 v89, v88, v89
	v_bfe_u32 v90, v89, 16, 1
	v_add3_u32 v89, v89, v90, s3
	ds_write_b16_d16_hi v218, v89 offset:15232
	v_and_b32_e32 v89, 0xffff0000, v64
	v_mul_f32_e32 v89, v88, v89
	v_bfe_u32 v90, v89, 16, 1
	v_add3_u32 v89, v89, v90, s3
	ds_write_b16_d16_hi v218, v89 offset:15504
	v_lshlrev_b32_e32 v89, 16, v65
	v_mul_f32_e32 v89, v88, v89
	v_bfe_u32 v90, v89, 16, 1
	v_add3_u32 v89, v89, v90, s3
	ds_write_b16_d16_hi v218, v89 offset:15776
	v_and_b32_e32 v89, 0xffff0000, v65
	v_mul_f32_e32 v89, v88, v89
	v_bfe_u32 v90, v89, 16, 1
	v_add3_u32 v89, v89, v90, s3
	ds_write_b16_d16_hi v218, v89 offset:16048
	v_lshlrev_b32_e32 v89, 16, v66
	v_mul_f32_e32 v89, v88, v89
	v_bfe_u32 v90, v89, 16, 1
	v_add3_u32 v89, v89, v90, s3
	ds_write_b16_d16_hi v218, v89 offset:16320
	v_and_b32_e32 v89, 0xffff0000, v66
	v_mul_f32_e32 v89, v88, v89
	v_bfe_u32 v90, v89, 16, 1
	v_add3_u32 v89, v89, v90, s3
	ds_write_b16_d16_hi v218, v89 offset:16592
	v_lshlrev_b32_e32 v89, 16, v67
	v_mul_f32_e32 v89, v88, v89
	v_bfe_u32 v90, v89, 16, 1
	v_add3_u32 v89, v89, v90, s3
	ds_write_b16_d16_hi v218, v89 offset:16864
	v_and_b32_e32 v89, 0xffff0000, v67
	v_mul_f32_e32 v88, v88, v89
	v_bfe_u32 v89, v88, 16, 1
	v_add3_u32 v88, v88, v89, s3
	ds_write_b16_d16_hi v218, v88 offset:17136
	s_cbranch_scc1 .LBB0_715
	v_add_u32_e32 v220, s97, v1
	v_ashrrev_i32_e32 v221, 31, v220
	v_lshlrev_b64 v[220:221], 13, v[220:221]
	v_lshl_add_u64 v[220:221], v[2:3], 0, v[220:221]
	v_lshl_add_u64 v[220:221], v[220:221], 0, v[214:215]
	global_load_dwordx4 v[8:11], v[220:221], off offset:2048
	global_load_dwordx4 v[16:19], v[220:221], off offset:2064
	global_load_dwordx4 v[24:27], v[220:221], off offset:2080
	global_load_dwordx4 v[32:35], v[220:221], off offset:2096
	global_load_dwordx4 v[40:43], v[220:221], off offset:2112
	global_load_dwordx4 v[48:51], v[220:221], off offset:2128
	global_load_dwordx4 v[56:59], v[220:221], off offset:2144
	global_load_dwordx4 v[64:67], v[220:221], off offset:2160

.LBB0_740:
	v_readlane_b32 s90, v244, 3
	v_readlane_b32 s62, v244, 0
	v_readlane_b32 s58, v245, 58
	v_readlane_b32 s56, v245, 60
	s_bitcmp0_b32 s82, 4
	v_readlane_b32 s88, v244, 7
	v_readlane_b32 s91, v244, 4
	v_readlane_b32 s61, v244, 2
	v_readlane_b32 s63, v244, 1
	v_readlane_b32 s59, v245, 59
	v_readlane_b32 s57, v245, 61
	v_readlane_b32 s60, v244, 8
	s_cbranch_scc1 .LBB0_762
	s_lshl_b32 s0, s92, 3
	s_add_i32 s10, s84, s0
	s_addk_i32 s10, 0xc00
	s_cmpk_gt_i32 s10, 0x7fff
	s_cbranch_scc1 .LBB0_762
	s_add_u32 s0, s96, 0xe800000
	s_addc_u32 s1, s97, 0
	s_add_u32 s8, s96, 0x10a40000
	s_addc_u32 s9, s97, 0
	v_readlane_b32 s12, v245, 6
	s_add_u32 s2, s96, 0x2f00000
	v_readlane_b32 s20, v245, 14
	s_addc_u32 s3, s97, 0
	v_readlane_b32 s13, v245, 7
	v_readlane_b32 s14, v245, 8
	v_readlane_b32 s15, v245, 9
	v_readlane_b32 s21, v245, 15
	s_add_u32 s20, s96, 0x17100000
	v_and_b32_e32 v2, 15, v208
	v_readlane_b32 s23, v245, 17
	s_addc_u32 s21, s97, 0
	v_readlane_b32 s12, v245, 0
	s_lshl_b32 s11, s60, 3
	v_mov_b32_e32 v1, 0
	v_lshlrev_b32_e32 v0, 4, v2
	v_readlane_b32 s18, v245, 12
	v_readlane_b32 s19, v245, 13
	v_readlane_b32 s13, v245, 1
	v_readlane_b32 s14, v245, 2
	v_readlane_b32 s15, v245, 3
	s_sub_i32 s23, 0, s11
	s_lshl_b32 s11, s88, 3
	v_readlane_b32 s24, v245, 18
	s_waitcnt vmcnt(0)
	v_lshl_add_u64 v[18:19], s[18:19], 0, v[0:1]
	v_lshl_add_u64 v[0:1], s[14:15], 0, v[0:1]
	s_mov_b64 s[12:13], 0x4ab1200
	s_add_i32 s11, s84, s11
	v_readlane_b32 s25, v245, 19
	v_readlane_b32 s26, v245, 20
	v_lshl_add_u64 v[20:21], v[0:1], 0, s[12:13]
	s_add_i32 s24, s11, 0xc00
	s_lshl_b32 s11, s33, 3
	s_lshl_b32 s12, s60, 4
	v_readlane_b32 s22, v245, 16
	v_readlane_b32 s27, v245, 21
	s_sub_i32 s25, s11, s12
	s_lshl_b32 s26, s10, 2
	s_lshl_b32 s10, s33, 6
	s_lshl_b32 s11, s60, 6
	v_lshrrev_b32_e32 v17, 4, v179
	v_lshlrev_b32_e32 v16, 2, v2
	v_cmp_ne_u32_e64 s[4:5], 0, v2
	v_cmp_eq_u32_e64 s[6:7], 0, v2
	s_lshl_b32 s22, s76, 4
	s_sub_i32 s27, s10, s11
	v_readlane_b32 s16, v245, 10
	v_readlane_b32 s17, v245, 11
	s_branch .LBB0_744

.LBB0_798:
	s_bitcmp0_b32 s82, 4
	s_cbranch_scc1 .LBB0_820
	s_lshl_b32 s0, s88, 3
	s_add_i32 s2, s84, s0
	s_cmp_gt_i32 s2, 0xbff
	s_cbranch_scc1 .LBB0_820
	v_readlane_b32 s4, v245, 6
	s_lshl_b32 s3, s60, 3
	v_readlane_b32 s6, v245, 8
	v_readlane_b32 s7, v245, 9
	s_add_u32 s6, s96, 0xe800000
	v_readlane_b32 s8, v245, 10
	s_addc_u32 s7, s97, 0
	v_readlane_b32 s9, v245, 11
	s_add_u32 s8, s96, 0x10a40000
	v_readlane_b32 s12, v245, 14
	v_readlane_b32 s13, v245, 15
	v_readlane_b32 s14, v245, 16
	v_readlane_b32 s15, v245, 17
	s_addc_u32 s9, s97, 0
	s_add_u32 s20, s96, 0x2f00000
	v_readlane_b32 s12, v245, 0
	s_waitcnt vmcnt(5)
	v_mov_b32_e32 v1, 0
	v_lshlrev_b32_e32 v0, 4, v70
	v_readlane_b32 s10, v245, 12
	v_readlane_b32 s11, v245, 13
	s_addc_u32 s21, s97, 0
	v_readlane_b32 s14, v245, 2
	v_readlane_b32 s15, v245, 3
	v_lshl_add_u64 v[18:19], s[10:11], 0, v[0:1]
	s_add_u32 s22, s96, 0x17100000
	v_lshl_add_u64 v[0:1], s[14:15], 0, v[0:1]
	s_mov_b64 s[10:11], 0x4ab1200
	v_readlane_b32 s5, v245, 7
	s_addc_u32 s23, s97, 0
	s_waitcnt vmcnt(4)
	v_lshl_add_u64 v[20:21], v[0:1], 0, s[10:11]
	s_lshl_b32 s10, s88, 5
	s_lshl_b32 s11, s84, 2
	v_lshlrev_b32_e32 v16, 2, v70
	v_cmp_ne_u32_e64 s[0:1], 0, v70
	v_cmp_eq_u32_e64 s[4:5], 0, v70
	s_lshl_b32 s24, s60, 4
	s_add_i32 s25, s10, s11
	s_lshl_b32 s26, s60, 6
	v_readlane_b32 s16, v245, 18
	v_readlane_b32 s17, v245, 19
	v_readlane_b32 s18, v245, 20
	v_readlane_b32 s19, v245, 21
	v_readlane_b32 s13, v245, 1
	s_branch .LBB0_802
.LBB0_801:
	s_add_i32 s2, s2, s24
	s_add_i32 s25, s25, s26
	s_cmp_gt_i32 s2, 0xbff
	s_cbranch_scc1 .LBB0_820
.LBB0_802:
	s_ashr_i32 s29, s2, 8
	s_lshl_b32 s10, s29, 10
	s_and_b32 s28, s25, 0x3c0
	v_readlane_b32 s36, v245, 6
	s_or_b32 s34, s28, s10
	s_mul_i32 s11, s29, 0x3480
	v_readlane_b32 s40, v245, 10
	s_mul_hi_i32 s10, s29, 0x3480
	v_readlane_b32 s41, v245, 11
	s_add_u32 s14, s40, s11
	s_addc_u32 s15, s41, s10
	s_add_i32 s18, s3, s2
	s_cmp_lt_i32 s18, 0xc00
	s_cselect_b64 s[10:11], -1, 0
	s_cmp_gt_i32 s18, 0xbff
	s_cselect_b64 s[12:13], -1, 0
	s_and_b64 s[16:17], s[12:13], exec
	s_cselect_b32 s16, s2, s18
	s_ashr_i32 s35, s16, 8
	s_lshl_b32 s36, s16, 2
	v_readlane_b32 s37, v245, 7
	s_lshl_b32 s16, s35, 10
	s_and_b32 s27, s36, 0x3c0
	s_or_b32 s37, s27, s16
	s_mul_i32 s17, s35, 0x3480
	s_mul_hi_i32 s16, s35, 0x3480
	s_add_u32 s18, s40, s17
	s_addc_u32 s19, s41, s16
	s_lshl_b32 s29, s29, 2
	s_add_i32 s16, s29, 0x2040
	s_ashr_i32 s17, s16, 31
	s_lshl_b64 s[30:31], s[16:17], 10
	s_or_b32 s30, s30, s28
	v_mov_b32_e32 v5, s31
	v_or_b32_e32 v4, s30, v16
	v_lshl_add_u64 v[0:1], v[4:5], 3, s[8:9]
	v_and_or_b32 v29, s25, 60, v61
	global_load_dwordx4 v[38:41], v[0:1], off
	global_load_dwordx4 v[42:45], v[0:1], off offset:16
	v_or_b32_e32 v0, s34, v29
	v_ashrrev_i32_e32 v1, 31, v0
	v_readlane_b32 s42, v245, 12
	v_readlane_b32 s43, v245, 13
	v_readlane_b32 s44, v245, 14
	v_readlane_b32 s45, v245, 15
	v_readlane_b32 s46, v245, 16
	v_readlane_b32 s47, v245, 17
	v_readlane_b32 s48, v245, 18
	v_readlane_b32 s49, v245, 19
	v_readlane_b32 s50, v245, 20
	v_readlane_b32 s51, v245, 21
	v_lshlrev_b64 v[22:23], 8, v[0:1]
	v_or_b32_e32 v0, s28, v29
	v_or_b32_e32 v0, 0x800, v0
	s_mul_i32 s30, s16, 0x3480
	v_readlane_b32 s40, v245, 22
	v_lshlrev_b32_e32 v27, 2, v0
	s_mul_hi_i32 s31, s16, 0x3480
	s_add_u32 s30, s20, s30
	v_readlane_b32 s41, v245, 23
	s_addc_u32 s31, s21, s31
	s_nop 3
	global_load_dword v26, v27, s[40:41]
	global_load_dword v33, v27, s[14:15]
	global_load_dword v32, v27, s[30:31]
	s_lshl_b32 s30, s35, 2
	s_add_i32 s14, s30, 0x2040
	v_lshl_add_u64 v[0:1], v[18:19], 0, v[22:23]
	v_and_or_b32 v30, s36, 60, v61
	s_ashr_i32 s15, s14, 31
	global_load_dwordx4 v[46:49], v[0:1], off
	v_or_b32_e32 v0, s37, v30
	s_lshl_b64 s[34:35], s[14:15], 10
	v_ashrrev_i32_e32 v1, 31, v0
	v_or_b32_e32 v6, s27, v30
	v_lshl_add_u64 v[4:5], v[4:5], 2, s[6:7]
	s_or_b32 s31, s34, s27
	v_lshlrev_b64 v[24:25], 8, v[0:1]
	v_or_b32_e32 v6, 0x800, v6
	global_load_dwordx4 v[50:53], v[4:5], off
	v_mov_b32_e32 v5, s35
	v_or_b32_e32 v4, s31, v16
	s_mul_i32 s34, s14, 0x3480
	v_lshl_add_u64 v[0:1], v[18:19], 0, v[24:25]
	v_lshlrev_b32_e32 v28, 2, v6
	v_lshl_add_u64 v[6:7], v[4:5], 2, s[6:7]
	v_lshl_add_u64 v[12:13], v[4:5], 3, s[8:9]
	s_mul_hi_i32 s31, s14, 0x3480
	s_add_u32 s34, s20, s34
	global_load_dwordx4 v[0:3], v[0:1], off
	s_nop 0
	global_load_dwordx4 v[8:11], v[12:13], off offset:16
	s_nop 0
	global_load_dwordx4 v[4:7], v[6:7], off
	s_nop 0
	global_load_dwordx4 v[12:15], v[12:13], off
	s_addc_u32 s35, s21, s31
	global_load_dword v17, v28, s[40:41]
	global_load_dword v37, v28, s[18:19]
	global_load_dword v31, v28, s[34:35]
	s_add_i32 s64, s29, 0x2041
	s_ashr_i32 s65, s64, 31
	s_lshl_b64 s[66:67], s[64:65], 10
	v_mov_b32_e32 v236, s28
	v_or3_b32 v236, s66, v236, v16
	v_or3_b32 v237, s67, 0, 0
	s_mul_hi_i32 s67, s64, 0x3480
	s_mul_i32 s66, s64, 0x3480
	s_add_u32 s66, s20, s66
	s_addc_u32 s67, s21, s67
	v_lshl_add_u64 v[238:239], v[236:237], 3, s[8:9]
	global_load_dwordx4 v[148:151], v[238:239], off
	global_load_dwordx4 v[152:155], v[238:239], off offset:16
	global_load_dword v172, v27, s[66:67]
	v_lshl_add_u64 v[238:239], v[236:237], 2, s[6:7]
	global_load_dwordx4 v[156:159], v[238:239], off
	s_add_i32 s64, s30, 0x2041
	s_ashr_i32 s65, s64, 31
	s_lshl_b64 s[66:67], s[64:65], 10
	v_mov_b32_e32 v236, s27
	v_or3_b32 v236, s66, v236, v16
	v_or3_b32 v237, s67, 0, 0
	s_mul_hi_i32 s67, s64, 0x3480
	s_mul_i32 s66, s64, 0x3480
	s_add_u32 s66, s20, s66
	s_addc_u32 s67, s21, s67
	v_lshl_add_u64 v[238:239], v[236:237], 3, s[8:9]
	global_load_dwordx4 v[160:163], v[238:239], off
	global_load_dwordx4 v[164:167], v[238:239], off offset:16
	global_load_dword v173, v28, s[66:67]
	v_lshl_add_u64 v[238:239], v[236:237], 2, s[6:7]
	global_load_dwordx4 v[168:171], v[238:239], off
	s_add_i32 s64, s29, 0x2042
	s_ashr_i32 s65, s64, 31
	s_lshl_b64 s[66:67], s[64:65], 10
	v_mov_b32_e32 v236, s28
	v_or3_b32 v236, s66, v236, v16
	v_or3_b32 v237, s67, 0, 0
	s_mul_hi_i32 s67, s64, 0x3480
	s_mul_i32 s66, s64, 0x3480
	s_add_u32 s66, s20, s66
	s_addc_u32 s67, s21, s67
	v_lshl_add_u64 v[238:239], v[236:237], 3, s[8:9]
	global_load_dwordx4 v[180:183], v[238:239], off
	global_load_dwordx4 v[184:187], v[238:239], off offset:16
	global_load_dword v204, v27, s[66:67]
	v_lshl_add_u64 v[238:239], v[236:237], 2, s[6:7]
	global_load_dwordx4 v[188:191], v[238:239], off
	s_add_i32 s64, s30, 0x2042
	s_ashr_i32 s65, s64, 31
	s_lshl_b64 s[66:67], s[64:65], 10
	v_mov_b32_e32 v236, s27
	v_or3_b32 v236, s66, v236, v16
	v_or3_b32 v237, s67, 0, 0
	s_mul_hi_i32 s67, s64, 0x3480
	s_mul_i32 s66, s64, 0x3480
	s_add_u32 s66, s20, s66
	s_addc_u32 s67, s21, s67
	v_lshl_add_u64 v[238:239], v[236:237], 3, s[8:9]
	global_load_dwordx4 v[192:195], v[238:239], off
	global_load_dwordx4 v[196:199], v[238:239], off offset:16
	global_load_dword v205, v28, s[66:67]
	v_lshl_add_u64 v[238:239], v[236:237], 2, s[6:7]
	global_load_dwordx4 v[200:203], v[238:239], off
	s_add_i32 s64, s29, 0x2043
	s_ashr_i32 s65, s64, 31
	s_lshl_b64 s[66:67], s[64:65], 10
	v_mov_b32_e32 v236, s28
	v_or3_b32 v236, s66, v236, v16
	v_or3_b32 v237, s67, 0, 0
	s_mul_hi_i32 s67, s64, 0x3480
	s_mul_i32 s66, s64, 0x3480
	s_add_u32 s66, s20, s66
	s_addc_u32 s67, s21, s67
	v_lshl_add_u64 v[238:239], v[236:237], 3, s[8:9]
	global_load_dwordx4 v[210:213], v[238:239], off
	global_load_dwordx4 v[214:217], v[238:239], off offset:16
	global_load_dword v234, v27, s[66:67]
	v_lshl_add_u64 v[238:239], v[236:237], 2, s[6:7]
	global_load_dwordx4 v[218:221], v[238:239], off
	s_add_i32 s64, s30, 0x2043
	s_ashr_i32 s65, s64, 31
	s_lshl_b64 s[66:67], s[64:65], 10
	v_mov_b32_e32 v236, s27
	v_or3_b32 v236, s66, v236, v16
	v_or3_b32 v237, s67, 0, 0
	s_mul_hi_i32 s67, s64, 0x3480
	s_mul_i32 s66, s64, 0x3480
	s_add_u32 s66, s20, s66
	s_addc_u32 s67, s21, s67
	v_lshl_add_u64 v[238:239], v[236:237], 3, s[8:9]
	global_load_dwordx4 v[222:225], v[238:239], off
	global_load_dwordx4 v[226:229], v[238:239], off offset:16
	global_load_dword v235, v28, s[66:67]
	v_lshl_add_u64 v[238:239], v[236:237], 2, s[6:7]
	global_load_dwordx4 v[230:233], v[238:239], off
	v_lshlrev_b32_e32 v29, 2, v29
	v_readlane_b32 s38, v245, 8
	v_readlane_b32 s39, v245, 9
	v_readlane_b32 s42, v245, 24
	v_readlane_b32 s43, v245, 25
	v_readlane_b32 s44, v245, 26
	v_readlane_b32 s45, v245, 27
	v_readlane_b32 s46, v245, 28
	v_readlane_b32 s47, v245, 29
	v_readlane_b32 s48, v245, 30
	v_readlane_b32 s49, v245, 31
	v_readlane_b32 s50, v245, 32
	v_readlane_b32 s51, v245, 33
	v_readlane_b32 s52, v245, 34
	v_readlane_b32 s53, v245, 35
	v_readlane_b32 s54, v245, 36
	v_readlane_b32 s55, v245, 37
	s_waitcnt vmcnt(37)
	v_lshlrev_b32_e32 v55, 16, v40
	v_and_b32_e32 v35, 0xffff0000, v40
	v_lshlrev_b32_e32 v40, 16, v39
	v_lshlrev_b32_e32 v54, 16, v38
	s_waitcnt vmcnt(36)
	v_lshlrev_b32_e32 v56, 16, v42
	v_lshlrev_b32_e32 v57, 16, v44
	v_and_b32_e32 v34, 0xffff0000, v38
	v_and_b32_e32 v36, 0xffff0000, v42
	v_and_b32_e32 v38, 0xffff0000, v44
	v_lshlrev_b32_e32 v42, 16, v41
	v_lshlrev_b32_e32 v44, 16, v43
	v_lshlrev_b32_e32 v58, 16, v45
	v_and_b32_e32 v39, 0xffff0000, v39
	v_and_b32_e32 v41, 0xffff0000, v41
	v_and_b32_e32 v43, 0xffff0000, v43
	v_and_b32_e32 v45, 0xffff0000, v45
	s_waitcnt vmcnt(33)
	v_sub_f32_e32 v33, v33, v32
	v_fma_f32 v59, v26, v33, v32
	s_waitcnt vmcnt(32)
	v_mul_f32 v33, v46, v40
	v_mul_f32 v40, v48, v44
	v_mul_f32 v34, v59, v34
	v_mul_f32 v35, v59, v35
	s_nop 0
	v_fma_f32 v33, v47, v42, v33
	v_fma_f32 v40, v49, v58, v40
	s_nop 0
	v_add_f32 v33, v33, v40
	s_nop 1
	v_add_f32_dpp v33, v33, v33 row_ror:8 row_mask:0xf bank_mask:0xf bound_ctrl:1
	s_nop 1
	v_add_f32_dpp v33, v33, v33 row_ror:4 row_mask:0xf bank_mask:0xf bound_ctrl:1
	s_nop 1
	v_add_f32_dpp v33, v33, v33 row_ror:2 row_mask:0xf bank_mask:0xf bound_ctrl:1
	s_nop 1
	v_add_f32_dpp v40, v33, v33 row_ror:1 row_mask:0xf bank_mask:0xf bound_ctrl:1
	v_fma_f32 v33, v40, v39, v34
	v_fma_f32 v34, v40, v41, v35
	v_mul_f32 v35, v59, v36
	v_mul_f32 v36, v59, v38
	s_waitcnt vmcnt(31)
	v_fma_f32 v33, v46, v50, v33
	v_fma_f32 v35, v40, v43, v35
	v_fma_f32 v34, v47, v51, v34
	v_fma_f32 v36, v40, v45, v36
	s_nop 0
	v_mul_f32 v38, v33, v54
	v_fma_f32 v35, v48, v52, v35
	v_fma_f32 v36, v49, v53, v36
	s_nop 0
	v_fma_f32 v38, v34, v55, v38
	v_mul_f32 v39, v35, v56
	s_nop 0
	v_fma_f32 v39, v36, v57, v39
	s_nop 0
	v_add_f32 v38, v38, v39
	v_mov_b32_e32 v39, 0
	s_nop 0
	v_add_f32_dpp v38, v38, v38 row_ror:8 row_mask:0xf bank_mask:0xf bound_ctrl:1
	s_nop 1
	v_add_f32_dpp v38, v38, v38 row_ror:4 row_mask:0xf bank_mask:0xf bound_ctrl:1
	s_nop 1
	v_add_f32_dpp v38, v38, v38 row_ror:2 row_mask:0xf bank_mask:0xf bound_ctrl:1
	s_nop 1
	v_mov_b32_dpp v39, v38 row_ror:1 row_mask:0xf bank_mask:0xf
	s_and_saveexec_b64 s[18:19], s[4:5]
	s_cbranch_execz .LBB0_804
	s_lshl_b64 s[16:17], s[16:17], 12
	s_add_u32 s16, s22, s16
	s_addc_u32 s17, s23, s17
	s_lshl_b32 s31, s28, 2
	s_add_u32 s16, s16, s31
	s_addc_u32 s17, s17, 0
	v_add_f32_e32 v38, v38, v39
	global_store_dword v29, v38, s[16:17]

	.amdhsa_kernel _Z3fwd4Args
		.amdhsa_group_segment_fixed_size 0
		.amdhsa_private_segment_fixed_size 0
		.amdhsa_kernarg_size 488
		.amdhsa_user_sgpr_count 2
		.amdhsa_user_sgpr_dispatch_ptr 0
		.amdhsa_user_sgpr_queue_ptr 0
		.amdhsa_user_sgpr_kernarg_segment_ptr 1
		.amdhsa_user_sgpr_dispatch_id 0
		.amdhsa_user_sgpr_kernarg_preload_length 0
		.amdhsa_user_sgpr_kernarg_preload_offset 0
		.amdhsa_user_sgpr_private_segment_size 0
		.amdhsa_uses_dynamic_stack 0
		.amdhsa_enable_private_segment 0
		.amdhsa_system_sgpr_workgroup_id_x 1
		.amdhsa_system_sgpr_workgroup_id_y 0
		.amdhsa_system_sgpr_workgroup_id_z 0
		.amdhsa_system_sgpr_workgroup_info 0
		.amdhsa_system_vgpr_workitem_id 2
		.amdhsa_next_free_vgpr 246
		.amdhsa_next_free_sgpr 102
		.amdhsa_accum_offset 248
		.amdhsa_reserve_vcc 1
		.amdhsa_float_round_mode_32 0
		.amdhsa_float_round_mode_16_64 0
		.amdhsa_float_denorm_mode_32 3
		.amdhsa_float_denorm_mode_16_64 3
		.amdhsa_dx10_clamp 1
		.amdhsa_ieee_mode 1
		.amdhsa_fp16_overflow 0
		.amdhsa_tg_split 0
		.amdhsa_exception_fp_ieee_invalid_op 0
		.amdhsa_exception_fp_denorm_src 0
		.amdhsa_exception_fp_ieee_div_zero 0
		.amdhsa_exception_fp_ieee_overflow 0
		.amdhsa_exception_fp_ieee_underflow 0
		.amdhsa_exception_fp_ieee_inexact 0
		.amdhsa_exception_int_div_zero 0
	.end_amdhsa_kernel

amdhsa.kernels:
  - .agpr_count:     0
    .args:
      - .offset:         0
        .size:           232
        .value_kind:     by_value
      - .offset:         232
        .size:           4
        .value_kind:     hidden_block_count_x
      - .offset:         236
        .size:           4
        .value_kind:     hidden_block_count_y
      - .offset:         240
        .size:           4
        .value_kind:     hidden_block_count_z
      - .offset:         244
        .size:           2
        .value_kind:     hidden_group_size_x
      - .offset:         246
        .size:           2
        .value_kind:     hidden_group_size_y
      - .offset:         248
        .size:           2
        .value_kind:     hidden_group_size_z
      - .offset:         250
        .size:           2
        .value_kind:     hidden_remainder_x
      - .offset:         252
        .size:           2
        .value_kind:     hidden_remainder_y
      - .offset:         254
        .size:           2
        .value_kind:     hidden_remainder_z
      - .offset:         272
        .size:           8
        .value_kind:     hidden_global_offset_x
      - .offset:         280
        .size:           8
        .value_kind:     hidden_global_offset_y
      - .offset:         288
        .size:           8
        .value_kind:     hidden_global_offset_z
      - .offset:         296
        .size:           2
        .value_kind:     hidden_grid_dims
      - .offset:         320
        .size:           8
        .value_kind:     hidden_multigrid_sync_arg
      - .offset:         352
        .size:           4
        .value_kind:     hidden_dynamic_lds_size
    .group_segment_fixed_size: 0
    .kernarg_segment_align: 8
    .kernarg_segment_size: 488
    .language:       OpenCL C
    .language_version:
      - 2
      - 0
    .max_flat_workgroup_size: 512
    .name:           _Z3fwd4Args
    .private_segment_fixed_size: 0
    .sgpr_count:     108
    .sgpr_spill_count: 76
    .symbol:         _Z3fwd4Args.kd
    .uniform_work_group_size: 1
    .uses_dynamic_stack: false
    .vgpr_count:     246
    .vgpr_spill_count: 0
    .wavefront_size: 64
